# GLA step 2: counted lgkmcnt waits before the per-d-tile LDS stores (next d-tile's loads stay in flight)
# baseline (speedup 1.0000x reference)
.Lqp_skip:
	v_mad_i64_i32 v[54:55], s[0:1], s58, v137, v[4:5]
	s_mov_b32 s69, s77
	v_lshl_add_u64 v[56:57], v[54:55], 0, s[76:77]
	v_lshl_add_u64 v[58:59], v[54:55], 0, s[68:69]
	v_lshl_add_u64 v[54:55], v[54:55], 0, s[98:99]
	global_load_dwordx4 v[86:89], v[56:57], off
	global_load_dwordx4 v[82:85], v[58:59], off
	v_lshl_add_u64 v[56:57], v[54:55], 0, s[76:77]
	v_lshl_add_u64 v[54:55], v[54:55], 0, s[68:69]
	global_load_dwordx4 v[78:81], v[56:57], off
	global_load_dwordx4 v[74:77], v[54:55], off
	v_mad_i64_i32 v[54:55], s[0:1], s58, v137, v[112:113]
	v_add_co_u32_e32 v56, vcc, 0x1000, v54
	s_nop 1
	v_addc_co_u32_e32 v57, vcc, 0, v55, vcc
	global_load_dwordx4 v[66:69], v[54:55], off
	global_load_dwordx4 v[58:61], v[54:55], off offset:128
	global_load_dwordx4 v[70:73], v[56:57], off offset:2112
	global_load_dwordx4 v[62:65], v[56:57], off offset:2240
	v_mad_i64_i32 v[54:55], s[0:1], s58, v137, v[114:115]
	global_load_dwordx4 v[54:57], v[54:55], off
	s_and_b64 vcc, exec, s[4:5]
	s_cbranch_vccnz .LBB0_314
	v_add3_u32 v98, v107, v186, 16
	v_add3_u32 v99, v107, v187, 16
	v_add3_u32 v100, v107, v190, 16
	v_add3_u32 v101, v107, v191, 16
	v_add3_u32 v102, v107, v194, 16
	v_add3_u32 v103, v107, v195, 16
	v_add3_u32 v104, v107, v198, 16
	v_add3_u32 v105, v107, v199, 16
	ds_read2st64_b32 v[220:221], v165 offset1:1
	ds_read2st64_b32 v[222:223], v165 offset0:2 offset1:3
	ds_read_u16 v236, v98
	ds_read_u16 v237, v98 offset:8192
	ds_read_u16 v238, v98 offset:128
	ds_read_u16 v239, v98 offset:8320
	ds_read_u16 v240, v99 offset:256
	ds_read_u16 v241, v99 offset:8448
	ds_read_u16 v242, v99 offset:384
	ds_read_u16 v243, v99 offset:8576
	s_waitcnt lgkmcnt(0)
	ds_read2st64_b32 v[224:225], v188 offset1:1
	ds_read2st64_b32 v[226:227], v188 offset0:2 offset1:3
	ds_read_u16 v244, v100
	ds_read_u16 v245, v100 offset:8192
	ds_read_u16 v246, v100 offset:128
	ds_read_u16 v247, v100 offset:8320
	ds_read_u16 v248, v101 offset:256
	ds_read_u16 v249, v101 offset:8448
	ds_read_u16 v250, v101 offset:384
	ds_read_u16 v251, v101 offset:8576
	v_add_f32_e32 v2, v220, v221
	v_add_f32_e32 v2, v2, v222
	v_add_f32_e32 v253, v2, v223
	v_mul_f32_e32 v223, 0x3fb8aa3b, v253
	v_exp_f32_e32 v223, v223
	v_cndmask_b32_e64 v2, 0, v220, s[18:19]
	v_cndmask_b32_e64 v220, 0, v221, s[14:15]
	v_add_f32_e32 v2, v2, v220
	v_cndmask_b32_e64 v220, 0, v222, s[20:21]
	v_add_f32_e32 v2, v2, v220
	v_add_f32_e32 v220, v95, v2
	v_sub_f32_e32 v221, v253, v220
	v_add_f32_e32 v2, v91, v220
	v_cndmask_b32_e64 v95, v221, v2, s[2:3]
	v_sub_f32_e32 v2, v221, v91
	v_add_f32_e32 v253, v94, v220
	v_cndmask_b32_e64 v91, v2, v253, s[2:3]
	v_sub_f32_e32 v2, v221, v94
	v_add_f32_e32 v253, v93, v220
	v_cndmask_b32_e64 v94, v2, v253, s[2:3]
	v_sub_f32_e32 v2, v221, v93
	v_add_f32_e32 v253, v92, v220
	v_cndmask_b32_e64 v93, v2, v253, s[2:3]
	v_mul_f32_e32 v95, 0x3fb8aa3b, v95
	v_mul_f32_e32 v91, 0x3fb8aa3b, v91
	v_mul_f32_e32 v94, 0x3fb8aa3b, v94
	v_mul_f32_e32 v93, 0x3fb8aa3b, v93
	v_exp_f32_e32 v95, v95
	v_exp_f32_e32 v91, v91
	v_exp_f32_e32 v94, v94
	v_exp_f32_e32 v93, v93
	v_rcp_f32_e32 v92, v95
	v_rcp_f32_e32 v220, v91
	v_rcp_f32_e32 v221, v94
	v_rcp_f32_e32 v222, v93
	s_waitcnt lgkmcnt(5)
	s_and_saveexec_b64 s[0:1], s[82:83]
	ds_write_b32 v185, v223
	s_or_b64 exec, exec, s[0:1]
	v_lshlrev_b32_e32 v2, 16, v236
	v_lshlrev_b32_e32 v253, 16, v237
	v_mul_f32_e32 v2, v95, v2
	v_mul_f32_e32 v253, v92, v253
	v_cvt_pk_bf16_f32 v236, v2, v253
	ds_write_b16 v98, v236
	ds_write_b16_d16_hi v98, v236 offset:8192
	v_mul_f32_e32 v95, v223, v253
	v_lshlrev_b32_e32 v2, 16, v238
	v_lshlrev_b32_e32 v253, 16, v239
	v_mul_f32_e32 v2, v91, v2
	v_mul_f32_e32 v253, v220, v253
	v_cvt_pk_bf16_f32 v238, v2, v253
	ds_write_b16 v98, v238 offset:128
	ds_write_b16_d16_hi v98, v238 offset:8320
	v_mul_f32_e32 v91, v223, v253
	v_lshlrev_b32_e32 v2, 16, v240
	v_lshlrev_b32_e32 v253, 16, v241
	v_mul_f32_e32 v2, v94, v2
	v_mul_f32_e32 v253, v221, v253
	v_cvt_pk_bf16_f32 v240, v2, v253
	ds_write_b16 v99, v240 offset:256
	ds_write_b16_d16_hi v99, v240 offset:8448
	v_mul_f32_e32 v94, v223, v253
	v_lshlrev_b32_e32 v2, 16, v242
	v_lshlrev_b32_e32 v253, 16, v243
	v_mul_f32_e32 v2, v93, v2
	v_mul_f32_e32 v253, v222, v253
	v_cvt_pk_bf16_f32 v242, v2, v253
	ds_write_b16 v99, v242 offset:384
	ds_write_b16_d16_hi v99, v242 offset:8576
	v_mul_f32_e32 v93, v223, v253
	v_cvt_pk_bf16_f32 v236, v95, v91
	v_cvt_pk_bf16_f32 v237, v94, v93
	v_add_u32_e32 v252, v182, v144
	ds_write_b64 v252, v[236:237] offset:16384
	s_waitcnt lgkmcnt(5)
	ds_read2st64_b32 v[228:229], v192 offset1:1
	ds_read2st64_b32 v[230:231], v192 offset0:2 offset1:3
	ds_read_u16 v236, v102
	ds_read_u16 v237, v102 offset:8192
	ds_read_u16 v238, v102 offset:128
	ds_read_u16 v239, v102 offset:8320
	ds_read_u16 v240, v103 offset:256
	ds_read_u16 v241, v103 offset:8448
	ds_read_u16 v242, v103 offset:384
	ds_read_u16 v243, v103 offset:8576
	v_add_f32_e32 v2, v224, v225
	v_add_f32_e32 v2, v2, v226
	v_add_f32_e32 v253, v2, v227
	v_mul_f32_e32 v227, 0x3fb8aa3b, v253
	v_exp_f32_e32 v227, v227
	v_cndmask_b32_e64 v2, 0, v224, s[18:19]
	v_cndmask_b32_e64 v224, 0, v225, s[14:15]
	v_add_f32_e32 v2, v2, v224
	v_cndmask_b32_e64 v224, 0, v226, s[20:21]
	v_add_f32_e32 v2, v2, v224
	v_add_f32_e32 v224, v211, v2
	v_sub_f32_e32 v225, v253, v224
	v_add_f32_e32 v2, v90, v224
	v_cndmask_b32_e64 v211, v225, v2, s[2:3]
	v_sub_f32_e32 v2, v225, v90
	v_add_f32_e32 v253, v210, v224
	v_cndmask_b32_e64 v90, v2, v253, s[2:3]
	v_sub_f32_e32 v2, v225, v210
	v_add_f32_e32 v253, v135, v224
	v_cndmask_b32_e64 v210, v2, v253, s[2:3]
	v_sub_f32_e32 v2, v225, v135
	v_add_f32_e32 v253, v209, v224
	v_cndmask_b32_e64 v135, v2, v253, s[2:3]
	v_mul_f32_e32 v211, 0x3fb8aa3b, v211
	v_mul_f32_e32 v90, 0x3fb8aa3b, v90
	v_mul_f32_e32 v210, 0x3fb8aa3b, v210
	v_mul_f32_e32 v135, 0x3fb8aa3b, v135
	v_exp_f32_e32 v211, v211
	v_exp_f32_e32 v90, v90
	v_exp_f32_e32 v210, v210
	v_exp_f32_e32 v135, v135
	v_rcp_f32_e32 v209, v211
	v_rcp_f32_e32 v224, v90
	v_rcp_f32_e32 v225, v210
	v_rcp_f32_e32 v226, v135
	s_waitcnt lgkmcnt(5)
	s_and_saveexec_b64 s[0:1], s[82:83]
	ds_write_b32 v189, v227
	s_or_b64 exec, exec, s[0:1]
	v_lshlrev_b32_e32 v2, 16, v244
	v_lshlrev_b32_e32 v253, 16, v245
	v_mul_f32_e32 v2, v211, v2
	v_mul_f32_e32 v253, v209, v253
	v_cvt_pk_bf16_f32 v244, v2, v253
	ds_write_b16 v100, v244
	ds_write_b16_d16_hi v100, v244 offset:8192
	v_mul_f32_e32 v211, v227, v253
	v_lshlrev_b32_e32 v2, 16, v246
	v_lshlrev_b32_e32 v253, 16, v247
	v_mul_f32_e32 v2, v90, v2
	v_mul_f32_e32 v253, v224, v253
	v_cvt_pk_bf16_f32 v246, v2, v253
	ds_write_b16 v100, v246 offset:128
	ds_write_b16_d16_hi v100, v246 offset:8320
	v_mul_f32_e32 v90, v227, v253
	v_lshlrev_b32_e32 v2, 16, v248
	v_lshlrev_b32_e32 v253, 16, v249
	v_mul_f32_e32 v2, v210, v2
	v_mul_f32_e32 v253, v225, v253
	v_cvt_pk_bf16_f32 v248, v2, v253
	ds_write_b16 v101, v248 offset:256
	ds_write_b16_d16_hi v101, v248 offset:8448
	v_mul_f32_e32 v210, v227, v253
	v_lshlrev_b32_e32 v2, 16, v250
	v_lshlrev_b32_e32 v253, 16, v251
	v_mul_f32_e32 v2, v135, v2
	v_mul_f32_e32 v253, v226, v253
	v_cvt_pk_bf16_f32 v250, v2, v253
	ds_write_b16 v101, v250 offset:384
	ds_write_b16_d16_hi v101, v250 offset:8576
	v_mul_f32_e32 v135, v227, v253
	v_cvt_pk_bf16_f32 v244, v211, v90
	v_cvt_pk_bf16_f32 v245, v210, v135
	ds_write_b64 v203, v[244:245] offset:16384
	s_waitcnt lgkmcnt(5)
	ds_read2st64_b32 v[232:233], v196 offset1:1
	ds_read2st64_b32 v[234:235], v196 offset0:2 offset1:3
	ds_read_u16 v244, v104
	ds_read_u16 v245, v104 offset:8192
	ds_read_u16 v246, v104 offset:128
	ds_read_u16 v247, v104 offset:8320
	ds_read_u16 v248, v105 offset:256
	ds_read_u16 v249, v105 offset:8448
	ds_read_u16 v250, v105 offset:384
	ds_read_u16 v251, v105 offset:8576
	v_add_f32_e32 v2, v228, v229
	v_add_f32_e32 v2, v2, v230
	v_add_f32_e32 v253, v2, v231
	v_mul_f32_e32 v231, 0x3fb8aa3b, v253
	v_exp_f32_e32 v231, v231
	v_cndmask_b32_e64 v2, 0, v228, s[18:19]
	v_cndmask_b32_e64 v228, 0, v229, s[14:15]
	v_add_f32_e32 v2, v2, v228
	v_cndmask_b32_e64 v228, 0, v230, s[20:21]
	v_add_f32_e32 v2, v2, v228
	v_add_f32_e32 v228, v215, v2
	v_sub_f32_e32 v229, v253, v228
	v_add_f32_e32 v2, v97, v228
	v_cndmask_b32_e64 v215, v229, v2, s[2:3]
	v_sub_f32_e32 v2, v229, v97
	v_add_f32_e32 v253, v214, v228
	v_cndmask_b32_e64 v97, v2, v253, s[2:3]
	v_sub_f32_e32 v2, v229, v214
	v_add_f32_e32 v253, v212, v228
	v_cndmask_b32_e64 v214, v2, v253, s[2:3]
	v_sub_f32_e32 v2, v229, v212
	v_add_f32_e32 v253, v213, v228
	v_cndmask_b32_e64 v212, v2, v253, s[2:3]
	v_mul_f32_e32 v215, 0x3fb8aa3b, v215
	v_mul_f32_e32 v97, 0x3fb8aa3b, v97
	v_mul_f32_e32 v214, 0x3fb8aa3b, v214
	v_mul_f32_e32 v212, 0x3fb8aa3b, v212
	v_exp_f32_e32 v215, v215
	v_exp_f32_e32 v97, v97
	v_exp_f32_e32 v214, v214
	v_exp_f32_e32 v212, v212
	v_rcp_f32_e32 v213, v215
	v_rcp_f32_e32 v228, v97
	v_rcp_f32_e32 v229, v214
	v_rcp_f32_e32 v230, v212
	s_waitcnt lgkmcnt(5)
	s_and_saveexec_b64 s[0:1], s[82:83]
	ds_write_b32 v193, v231
	s_or_b64 exec, exec, s[0:1]
	v_lshlrev_b32_e32 v2, 16, v236
	v_lshlrev_b32_e32 v253, 16, v237
	v_mul_f32_e32 v2, v215, v2
	v_mul_f32_e32 v253, v213, v253
	v_cvt_pk_bf16_f32 v236, v2, v253
	ds_write_b16 v102, v236
	ds_write_b16_d16_hi v102, v236 offset:8192
	v_mul_f32_e32 v215, v231, v253
	v_lshlrev_b32_e32 v2, 16, v238
	v_lshlrev_b32_e32 v253, 16, v239
	v_mul_f32_e32 v2, v97, v2
	v_mul_f32_e32 v253, v228, v253
	v_cvt_pk_bf16_f32 v238, v2, v253
	ds_write_b16 v102, v238 offset:128
	ds_write_b16_d16_hi v102, v238 offset:8320
	v_mul_f32_e32 v97, v231, v253
	v_lshlrev_b32_e32 v2, 16, v240
	v_lshlrev_b32_e32 v253, 16, v241
	v_mul_f32_e32 v2, v214, v2
	v_mul_f32_e32 v253, v229, v253
	v_cvt_pk_bf16_f32 v240, v2, v253
	ds_write_b16 v103, v240 offset:256
	ds_write_b16_d16_hi v103, v240 offset:8448
	v_mul_f32_e32 v214, v231, v253
	v_lshlrev_b32_e32 v2, 16, v242
	v_lshlrev_b32_e32 v253, 16, v243
	v_mul_f32_e32 v2, v212, v2
	v_mul_f32_e32 v253, v230, v253
	v_cvt_pk_bf16_f32 v242, v2, v253
	ds_write_b16 v103, v242 offset:384
	ds_write_b16_d16_hi v103, v242 offset:8576
	v_mul_f32_e32 v212, v231, v253
	v_cvt_pk_bf16_f32 v236, v215, v97
	v_cvt_pk_bf16_f32 v237, v214, v212
	ds_write_b64 v204, v[236:237] offset:16384
	v_add_f32_e32 v2, v232, v233
	v_add_f32_e32 v2, v2, v234
	v_add_f32_e32 v253, v2, v235
	v_mul_f32_e32 v235, 0x3fb8aa3b, v253
	v_exp_f32_e32 v235, v235
	v_cndmask_b32_e64 v2, 0, v232, s[18:19]
	v_cndmask_b32_e64 v232, 0, v233, s[14:15]
	v_add_f32_e32 v2, v2, v232
	v_cndmask_b32_e64 v232, 0, v234, s[20:21]
	v_add_f32_e32 v2, v2, v232
	v_add_f32_e32 v232, v219, v2
	v_sub_f32_e32 v233, v253, v232
	v_add_f32_e32 v2, v96, v232
	v_cndmask_b32_e64 v219, v233, v2, s[2:3]
	v_sub_f32_e32 v2, v233, v96
	v_add_f32_e32 v253, v218, v232
	v_cndmask_b32_e64 v96, v2, v253, s[2:3]
	v_sub_f32_e32 v2, v233, v218
	v_add_f32_e32 v253, v216, v232
	v_cndmask_b32_e64 v218, v2, v253, s[2:3]
	v_sub_f32_e32 v2, v233, v216
	v_add_f32_e32 v253, v217, v232
	v_cndmask_b32_e64 v216, v2, v253, s[2:3]
	v_mul_f32_e32 v219, 0x3fb8aa3b, v219
	v_mul_f32_e32 v96, 0x3fb8aa3b, v96
	v_mul_f32_e32 v218, 0x3fb8aa3b, v218
	v_mul_f32_e32 v216, 0x3fb8aa3b, v216
	v_exp_f32_e32 v219, v219
	v_exp_f32_e32 v96, v96
	v_exp_f32_e32 v218, v218
	v_exp_f32_e32 v216, v216
	v_rcp_f32_e32 v217, v219
	v_rcp_f32_e32 v232, v96
	v_rcp_f32_e32 v233, v218
	v_rcp_f32_e32 v234, v216
	s_waitcnt lgkmcnt(0)
	s_and_saveexec_b64 s[0:1], s[82:83]
	ds_write_b32 v197, v235
	s_or_b64 exec, exec, s[0:1]
	v_lshlrev_b32_e32 v2, 16, v244
	v_lshlrev_b32_e32 v253, 16, v245
	v_mul_f32_e32 v2, v219, v2
	v_mul_f32_e32 v253, v217, v253
	v_cvt_pk_bf16_f32 v244, v2, v253
	ds_write_b16 v104, v244
	ds_write_b16_d16_hi v104, v244 offset:8192
	v_mul_f32_e32 v219, v235, v253
	v_lshlrev_b32_e32 v2, 16, v246
	v_lshlrev_b32_e32 v253, 16, v247
	v_mul_f32_e32 v2, v96, v2
	v_mul_f32_e32 v253, v232, v253
	v_cvt_pk_bf16_f32 v246, v2, v253
	ds_write_b16 v104, v246 offset:128
	ds_write_b16_d16_hi v104, v246 offset:8320
	v_mul_f32_e32 v96, v235, v253
	v_lshlrev_b32_e32 v2, 16, v248
	v_lshlrev_b32_e32 v253, 16, v249
	v_mul_f32_e32 v2, v218, v2
	v_mul_f32_e32 v253, v233, v253
	v_cvt_pk_bf16_f32 v248, v2, v253
	ds_write_b16 v105, v248 offset:256
	ds_write_b16_d16_hi v105, v248 offset:8448
	v_mul_f32_e32 v218, v235, v253
	v_lshlrev_b32_e32 v2, 16, v250
	v_lshlrev_b32_e32 v253, 16, v251
	v_mul_f32_e32 v2, v216, v2
	v_mul_f32_e32 v253, v234, v253
	v_cvt_pk_bf16_f32 v250, v2, v253
	ds_write_b16 v105, v250 offset:384
	ds_write_b16_d16_hi v105, v250 offset:8576
	v_mul_f32_e32 v216, v235, v253
	v_cvt_pk_bf16_f32 v244, v219, v96
	v_cvt_pk_bf16_f32 v245, v218, v216
	ds_write_b64 v205, v[244:245] offset:16384
	s_waitcnt lgkmcnt(0)
	s_barrier
